# attention item epilogues (phases 3 and 4): 8-byte row-per-lane output stores transposed through wave-private LDS into coalesced dwordx4 stores
# speedup vs baseline: 1.0473x; 1.0067x over previous
.LBB0_759:
	s_or_b64 exec, exec, s[14:15]
	ds_bpermute_b32 v4, v234, v10
	v_and_b32_e32 v5, 0xffff0000, v128
	v_lshl_add_u64 v[2:3], v[126:127], 1, v[130:131]
	v_lshl_add_u64 v[2:3], v[2:3], 0, v[0:1]
	s_waitcnt lgkmcnt(0)
	v_add_f32_e32 v4, v10, v4
	v_max_f32_e32 v6, 0xda24260, v4
	v_div_scale_f32 v7, s[14:15], v6, v6, 1.0
	v_rcp_f32_e32 v8, v7
	v_div_scale_f32 v9, vcc, 1.0, v6, 1.0
	v_lshlrev_b32_e32 v4, 16, v128
	v_fma_f32 v10, -v7, v8, 1.0
	v_fmac_f32_e32 v8, v10, v8
	v_mul_f32_e32 v10, v9, v8
	v_fma_f32 v11, -v7, v10, v9
	v_fmac_f32_e32 v10, v11, v8
	v_fma_f32 v7, -v7, v10, v9
	v_div_fmas_f32 v7, v7, v8, v10
	v_div_fixup_f32 v6, v7, v6, 1.0
	v_pk_mul_f32 v[8:9], v[32:33], v[6:7] op_sel_hi:[1,0]
	v_pk_mul_f32 v[10:11], v[34:35], v[6:7] op_sel_hi:[1,0]
	v_pk_mul_f32 v[4:5], v[8:9], v[4:5]
	v_and_b32_e32 v9, 0xffff0000, v129
	v_lshlrev_b32_e32 v8, 16, v129
	v_pk_mul_f32 v[8:9], v[10:11], v[8:9]
	s_mov_b64 s[14:15], 0x16f80400
	v_cvt_pk_bf16_f32 v4, v4, v5
	v_cvt_pk_bf16_f32 v5, v8, v9
	v_lshl_add_u64 v[8:9], v[2:3], 0, s[14:15]
	s_mov_b32 s14, 0x16f80000
	v_add_co_u32_e32 v2, vcc, s14, v2
	v_pk_mul_f32 v[10:11], v[38:39], v[6:7] op_sel_hi:[1,0]
	s_nop 0
	v_addc_co_u32_e32 v3, vcc, 0, v3, vcc
	v_lshrrev_b32_e32 v216, 6, v140
	v_mul_u32_u24_e32 v216, 0x1200, v216
	v_add_u32_e32 v216, v216, v141
	v_add_u32_e32 v216, 0x3000, v216
	v_and_b32_e32 v218, 31, v198
	v_lshrrev_b32_e32 v219, 5, v198
	v_lshrrev_b32_e32 v220, 3, v198
	v_and_b32_e32 v221, 7, v198
	v_mul_u32_u24_e32 v222, 0x90, v220
	v_lshl_add_u32 v222, v221, 4, v222
	v_add_u32_e32 v217, v222, v216
	v_mul_u32_u24_e32 v222, 0x90, v218
	v_lshl_add_u32 v222, v219, 3, v222
	v_add_u32_e32 v216, v222, v216
	v_sub_u32_e32 v220, v220, v218
	v_lshlrev_b32_e32 v220, 11, v220
	v_lshl_add_u32 v220, v221, 4, v220
	v_lshlrev_b32_e32 v219, 3, v219
	v_sub_u32_e32 v220, v220, v219
	v_ashrrev_i32_e32 v221, 31, v220
	v_lshl_add_u64 v[218:219], v[8:9], 0, v[220:221]
	ds_write_b64 v216, v[4:5]
	v_and_b32_e32 v3, 0xffff0000, v124
	v_lshlrev_b32_e32 v2, 16, v124
	v_pk_mul_f32 v[4:5], v[36:37], v[6:7] op_sel_hi:[1,0]
	s_nop 0
	v_pk_mul_f32 v[2:3], v[4:5], v[2:3]
	v_and_b32_e32 v5, 0xffff0000, v125
	v_lshlrev_b32_e32 v4, 16, v125
	v_pk_mul_f32 v[4:5], v[10:11], v[4:5]
	v_cvt_pk_bf16_f32 v2, v2, v3
	v_cvt_pk_bf16_f32 v3, v4, v5
	ds_write_b64 v216, v[2:3] offset:16
	v_and_b32_e32 v3, 0xffff0000, v122
	v_lshlrev_b32_e32 v2, 16, v122
	v_pk_mul_f32 v[4:5], v[40:41], v[6:7] op_sel_hi:[1,0]
	v_pk_mul_f32 v[10:11], v[42:43], v[6:7] op_sel_hi:[1,0]
	v_pk_mul_f32 v[2:3], v[4:5], v[2:3]
	v_and_b32_e32 v5, 0xffff0000, v123
	v_lshlrev_b32_e32 v4, 16, v123
	v_pk_mul_f32 v[4:5], v[10:11], v[4:5]
	v_cvt_pk_bf16_f32 v2, v2, v3
	v_cvt_pk_bf16_f32 v3, v4, v5
	ds_write_b64 v216, v[2:3] offset:32
	v_and_b32_e32 v3, 0xffff0000, v120
	v_lshlrev_b32_e32 v2, 16, v120
	v_pk_mul_f32 v[4:5], v[44:45], v[6:7] op_sel_hi:[1,0]
	v_pk_mul_f32 v[10:11], v[46:47], v[6:7] op_sel_hi:[1,0]
	v_pk_mul_f32 v[2:3], v[4:5], v[2:3]
	v_and_b32_e32 v5, 0xffff0000, v121
	v_lshlrev_b32_e32 v4, 16, v121
	v_pk_mul_f32 v[4:5], v[10:11], v[4:5]
	v_cvt_pk_bf16_f32 v2, v2, v3
	v_cvt_pk_bf16_f32 v3, v4, v5
	ds_write_b64 v216, v[2:3] offset:48
	v_and_b32_e32 v3, 0xffff0000, v118
	v_lshlrev_b32_e32 v2, 16, v118
	v_pk_mul_f32 v[4:5], v[16:17], v[6:7] op_sel_hi:[1,0]
	v_pk_mul_f32 v[10:11], v[18:19], v[6:7] op_sel_hi:[1,0]
	v_pk_mul_f32 v[2:3], v[4:5], v[2:3]
	v_and_b32_e32 v5, 0xffff0000, v119
	v_lshlrev_b32_e32 v4, 16, v119
	v_pk_mul_f32 v[4:5], v[10:11], v[4:5]
	v_cvt_pk_bf16_f32 v2, v2, v3
	v_cvt_pk_bf16_f32 v3, v4, v5
	ds_write_b64 v216, v[2:3] offset:64
	v_and_b32_e32 v3, 0xffff0000, v116
	v_lshlrev_b32_e32 v2, 16, v116
	v_pk_mul_f32 v[4:5], v[20:21], v[6:7] op_sel_hi:[1,0]
	v_pk_mul_f32 v[10:11], v[22:23], v[6:7] op_sel_hi:[1,0]
	v_pk_mul_f32 v[2:3], v[4:5], v[2:3]
	v_and_b32_e32 v5, 0xffff0000, v117
	v_lshlrev_b32_e32 v4, 16, v117
	v_pk_mul_f32 v[4:5], v[10:11], v[4:5]
	v_cvt_pk_bf16_f32 v2, v2, v3
	v_cvt_pk_bf16_f32 v3, v4, v5
	ds_write_b64 v216, v[2:3] offset:80
	v_and_b32_e32 v3, 0xffff0000, v114
	v_lshlrev_b32_e32 v2, 16, v114
	v_pk_mul_f32 v[4:5], v[24:25], v[6:7] op_sel_hi:[1,0]
	v_pk_mul_f32 v[10:11], v[26:27], v[6:7] op_sel_hi:[1,0]
	v_pk_mul_f32 v[2:3], v[4:5], v[2:3]
	v_and_b32_e32 v5, 0xffff0000, v115
	v_lshlrev_b32_e32 v4, 16, v115
	v_pk_mul_f32 v[4:5], v[10:11], v[4:5]
	v_cvt_pk_bf16_f32 v2, v2, v3
	v_cvt_pk_bf16_f32 v3, v4, v5
	ds_write_b64 v216, v[2:3] offset:96
	v_and_b32_e32 v3, 0xffff0000, v112
	v_lshlrev_b32_e32 v2, 16, v112
	v_pk_mul_f32 v[4:5], v[28:29], v[6:7] op_sel_hi:[1,0]
	v_pk_mul_f32 v[6:7], v[30:31], v[6:7] op_sel_hi:[1,0]
	v_pk_mul_f32 v[2:3], v[4:5], v[2:3]
	v_and_b32_e32 v5, 0xffff0000, v113
	v_lshlrev_b32_e32 v4, 16, v113
	v_pk_mul_f32 v[4:5], v[6:7], v[4:5]
	v_cvt_pk_bf16_f32 v2, v2, v3
	v_cvt_pk_bf16_f32 v3, v4, v5
	ds_write_b64 v216, v[2:3] offset:112
	s_waitcnt lgkmcnt(0)
	ds_read_b128 v[200:203], v217
	ds_read_b128 v[204:207], v217 offset:1152
	ds_read_b128 v[208:211], v217 offset:2304
	ds_read_b128 v[212:215], v217 offset:3456
	v_mov_b32_e32 v220, 0x4000
	v_mov_b32_e32 v221, 0
	s_waitcnt lgkmcnt(3)
	global_store_dwordx4 v[218:219], v[200:203], off
	v_lshl_add_u64 v[218:219], v[218:219], 0, v[220:221]
	s_waitcnt lgkmcnt(2)
	global_store_dwordx4 v[218:219], v[204:207], off
	v_lshl_add_u64 v[218:219], v[218:219], 0, v[220:221]
	s_waitcnt lgkmcnt(1)
	global_store_dwordx4 v[218:219], v[208:211], off
	v_lshl_add_u64 v[218:219], v[218:219], 0, v[220:221]
	s_waitcnt lgkmcnt(0)
	global_store_dwordx4 v[218:219], v[212:215], off
	s_barrier

.LBB0_907:
	s_or_b64 exec, exec, s[18:19]
	ds_bpermute_b32 v0, v234, v10
	s_waitcnt vmcnt(6)
	v_and_b32_e32 v5, 0xffff0000, v122
	v_lshlrev_b32_e32 v4, 16, v122
	v_lshl_add_u64 v[2:3], v[118:119], 1, v[120:121]
	s_waitcnt lgkmcnt(0)
	v_add_f32_e32 v0, v10, v0
	v_max_f32_e32 v0, 0xda24260, v0
	v_div_scale_f32 v6, s[18:19], v0, v0, 1.0
	v_rcp_f32_e32 v7, v6
	v_div_scale_f32 v8, vcc, 1.0, v0, 1.0
	s_mov_b64 s[18:19], 0x16f80400
	v_fma_f32 v9, -v6, v7, 1.0
	v_fmac_f32_e32 v7, v9, v7
	v_mul_f32_e32 v9, v8, v7
	v_fma_f32 v10, -v6, v9, v8
	v_fmac_f32_e32 v9, v10, v7
	v_fma_f32 v6, -v6, v9, v8
	v_div_fmas_f32 v6, v6, v7, v9
	v_div_fixup_f32 v6, v6, v0, 1.0
	v_pk_mul_f32 v[8:9], v[32:33], v[6:7] op_sel_hi:[1,0]
	v_pk_mul_f32 v[10:11], v[34:35], v[6:7] op_sel_hi:[1,0]
	v_pk_mul_f32 v[4:5], v[8:9], v[4:5]
	v_and_b32_e32 v9, 0xffff0000, v123
	v_lshlrev_b32_e32 v8, 16, v123
	v_lshlrev_b32_e32 v0, 1, v125
	v_pk_mul_f32 v[8:9], v[10:11], v[8:9]
	v_lshl_add_u64 v[2:3], v[2:3], 0, v[0:1]
	v_cvt_pk_bf16_f32 v4, v4, v5
	v_cvt_pk_bf16_f32 v5, v8, v9
	v_lshl_add_u64 v[8:9], v[2:3], 0, s[18:19]
	s_mov_b32 s18, 0x16f80000
	v_add_co_u32_e32 v2, vcc, s18, v2
	v_pk_mul_f32 v[10:11], v[38:39], v[6:7] op_sel_hi:[1,0]
	s_nop 0
	v_addc_co_u32_e32 v3, vcc, 0, v3, vcc
	v_lshrrev_b32_e32 v216, 6, v172
	v_mul_u32_u24_e32 v216, 0x1200, v216
	v_add_u32_e32 v216, v216, v182
	v_add_u32_e32 v216, 0x3000, v216
	v_and_b32_e32 v218, 31, v198
	v_lshrrev_b32_e32 v219, 5, v198
	v_lshrrev_b32_e32 v220, 3, v198
	v_and_b32_e32 v221, 7, v198
	v_mul_u32_u24_e32 v222, 0x90, v220
	v_lshl_add_u32 v222, v221, 4, v222
	v_add_u32_e32 v217, v222, v216
	v_mul_u32_u24_e32 v222, 0x90, v218
	v_lshl_add_u32 v222, v219, 3, v222
	v_add_u32_e32 v216, v222, v216
	v_sub_u32_e32 v220, v220, v218
	v_lshlrev_b32_e32 v220, 11, v220
	v_lshl_add_u32 v220, v221, 4, v220
	v_lshlrev_b32_e32 v219, 3, v219
	v_sub_u32_e32 v220, v220, v219
	v_ashrrev_i32_e32 v221, 31, v220
	v_lshl_add_u64 v[218:219], v[8:9], 0, v[220:221]
	ds_write_b64 v216, v[4:5]
	v_and_b32_e32 v3, 0xffff0000, v116
	v_lshlrev_b32_e32 v2, 16, v116
	v_pk_mul_f32 v[4:5], v[36:37], v[6:7] op_sel_hi:[1,0]
	s_nop 0
	v_pk_mul_f32 v[2:3], v[4:5], v[2:3]
	v_and_b32_e32 v5, 0xffff0000, v117
	v_lshlrev_b32_e32 v4, 16, v117
	v_pk_mul_f32 v[4:5], v[10:11], v[4:5]
	v_cvt_pk_bf16_f32 v2, v2, v3
	v_cvt_pk_bf16_f32 v3, v4, v5
	ds_write_b64 v216, v[2:3] offset:16
	v_and_b32_e32 v3, 0xffff0000, v114
	v_lshlrev_b32_e32 v2, 16, v114
	v_pk_mul_f32 v[4:5], v[40:41], v[6:7] op_sel_hi:[1,0]
	v_pk_mul_f32 v[10:11], v[42:43], v[6:7] op_sel_hi:[1,0]
	v_pk_mul_f32 v[2:3], v[4:5], v[2:3]
	v_and_b32_e32 v5, 0xffff0000, v115
	v_lshlrev_b32_e32 v4, 16, v115
	v_pk_mul_f32 v[4:5], v[10:11], v[4:5]
	v_cvt_pk_bf16_f32 v2, v2, v3
	v_cvt_pk_bf16_f32 v3, v4, v5
	ds_write_b64 v216, v[2:3] offset:32
	v_and_b32_e32 v3, 0xffff0000, v112
	v_lshlrev_b32_e32 v2, 16, v112
	v_pk_mul_f32 v[4:5], v[44:45], v[6:7] op_sel_hi:[1,0]
	v_pk_mul_f32 v[10:11], v[46:47], v[6:7] op_sel_hi:[1,0]
	v_pk_mul_f32 v[2:3], v[4:5], v[2:3]
	v_and_b32_e32 v5, 0xffff0000, v113
	v_lshlrev_b32_e32 v4, 16, v113
	v_pk_mul_f32 v[4:5], v[10:11], v[4:5]
	v_cvt_pk_bf16_f32 v2, v2, v3
	v_cvt_pk_bf16_f32 v3, v4, v5
	ds_write_b64 v216, v[2:3] offset:48
	v_and_b32_e32 v3, 0xffff0000, v110
	v_lshlrev_b32_e32 v2, 16, v110
	v_pk_mul_f32 v[4:5], v[16:17], v[6:7] op_sel_hi:[1,0]
	v_pk_mul_f32 v[10:11], v[18:19], v[6:7] op_sel_hi:[1,0]
	v_pk_mul_f32 v[2:3], v[4:5], v[2:3]
	v_and_b32_e32 v5, 0xffff0000, v111
	v_lshlrev_b32_e32 v4, 16, v111
	v_pk_mul_f32 v[4:5], v[10:11], v[4:5]
	v_cvt_pk_bf16_f32 v2, v2, v3
	v_cvt_pk_bf16_f32 v3, v4, v5
	ds_write_b64 v216, v[2:3] offset:64
	v_and_b32_e32 v3, 0xffff0000, v108
	v_lshlrev_b32_e32 v2, 16, v108
	v_pk_mul_f32 v[4:5], v[20:21], v[6:7] op_sel_hi:[1,0]
	v_pk_mul_f32 v[10:11], v[22:23], v[6:7] op_sel_hi:[1,0]
	v_pk_mul_f32 v[2:3], v[4:5], v[2:3]
	v_and_b32_e32 v5, 0xffff0000, v109
	v_lshlrev_b32_e32 v4, 16, v109
	v_pk_mul_f32 v[4:5], v[10:11], v[4:5]
	v_cvt_pk_bf16_f32 v2, v2, v3
	v_cvt_pk_bf16_f32 v3, v4, v5
	ds_write_b64 v216, v[2:3] offset:80
	s_waitcnt vmcnt(5)
	v_and_b32_e32 v3, 0xffff0000, v106
	v_lshlrev_b32_e32 v2, 16, v106
	v_pk_mul_f32 v[4:5], v[24:25], v[6:7] op_sel_hi:[1,0]
	v_pk_mul_f32 v[10:11], v[26:27], v[6:7] op_sel_hi:[1,0]
	v_pk_mul_f32 v[2:3], v[4:5], v[2:3]
	v_and_b32_e32 v5, 0xffff0000, v107
	v_lshlrev_b32_e32 v4, 16, v107
	v_pk_mul_f32 v[4:5], v[10:11], v[4:5]
	v_cvt_pk_bf16_f32 v2, v2, v3
	v_cvt_pk_bf16_f32 v3, v4, v5
	ds_write_b64 v216, v[2:3] offset:96
	s_waitcnt vmcnt(4)
	v_and_b32_e32 v3, 0xffff0000, v104
	v_lshlrev_b32_e32 v2, 16, v104
	v_pk_mul_f32 v[4:5], v[28:29], v[6:7] op_sel_hi:[1,0]
	v_pk_mul_f32 v[6:7], v[30:31], v[6:7] op_sel_hi:[1,0]
	v_pk_mul_f32 v[2:3], v[4:5], v[2:3]
	v_and_b32_e32 v5, 0xffff0000, v105
	v_lshlrev_b32_e32 v4, 16, v105
	v_pk_mul_f32 v[4:5], v[6:7], v[4:5]
	v_cvt_pk_bf16_f32 v2, v2, v3
	v_cvt_pk_bf16_f32 v3, v4, v5
	ds_write_b64 v216, v[2:3] offset:112
	s_waitcnt lgkmcnt(0)
	ds_read_b128 v[200:203], v217
	ds_read_b128 v[204:207], v217 offset:1152
	ds_read_b128 v[208:211], v217 offset:2304
	ds_read_b128 v[212:215], v217 offset:3456
	v_mov_b32_e32 v220, 0x4000
	v_mov_b32_e32 v221, 0
	s_waitcnt lgkmcnt(3)
	global_store_dwordx4 v[218:219], v[200:203], off
	v_lshl_add_u64 v[218:219], v[218:219], 0, v[220:221]
	s_waitcnt lgkmcnt(2)
	global_store_dwordx4 v[218:219], v[204:207], off
	v_lshl_add_u64 v[218:219], v[218:219], 0, v[220:221]
	s_waitcnt lgkmcnt(1)
	global_store_dwordx4 v[218:219], v[208:211], off
	v_lshl_add_u64 v[218:219], v[218:219], 0, v[220:221]
	s_waitcnt lgkmcnt(0)
	global_store_dwordx4 v[218:219], v[212:215], off
	s_barrier
